# chain K-loop back edge rotated: loop counter, exit test and next-iteration head tests computed with SALU in the last MFMA block's shadow, one SCC branch after the closing barrier straight to the next
# speedup vs baseline: 1.0050x; 1.0002x over previous
.LBB0_389:
	v_cndmask_b32_e64 v148, 0, 1, s[70:71]
	v_cmp_ne_u32_e64 s[8:9], 1, v148
	s_andn2_b64 vcc, exec, s[70:71]
	s_cbranch_vccnz .LBB0_391
	s_mov_b32 m0, s82
	s_nop 0
	global_load_lds_dword v165, s[68:69] sc1
	s_branch .LBB0_391
.Lk_fastb:
	s_mov_b32 s22, s32
.LBB0_391:
	ds_read_b128 v[148:151], v144
	ds_read_b128 v[152:155], v144 offset:1024
	ds_read_b128 v[156:159], v144 offset:2048
	ds_read_b128 v[160:163], v144 offset:3072
	ds_read_b128 v[174:177], v145
	ds_read_b128 v[178:181], v145 offset:1024
	ds_read_b128 v[182:185], v145 offset:2048
	ds_read_b128 v[186:189], v145 offset:3072
	v_lshl_add_u64 v[236:237], v[142:143], 0, s[62:63]
	s_mov_b32 m0, s55
	v_lshl_add_u64 v[238:239], v[236:237], 0, s[44:45]
	ds_read_b128 v[190:193], v195
	ds_read_b128 v[208:211], v195 offset:1024
	ds_read_b128 v[212:215], v195 offset:2048
	ds_read_b128 v[216:219], v195 offset:3072
	ds_read_b128 v[220:223], v195 offset:4096
	ds_read_b128 v[224:227], v195 offset:5120
	ds_read_b128 v[228:231], v195 offset:6144
	ds_read_b128 v[232:235], v195 offset:7168
	global_load_lds_dwordx4 v[238:239], off
	v_lshl_add_u64 v[238:239], v[140:141], 0, s[62:63]
	v_lshl_add_u64 v[240:241], v[238:239], 0, s[44:45]
	s_mov_b32 m0, s97
	s_nop 0
	global_load_lds_dwordx4 v[240:241], off
	s_waitcnt vmcnt(8)
	s_waitcnt lgkmcnt(0)
	s_barrier
	s_setprio 1
	s_waitcnt lgkmcnt(0)
	v_mfma_f32_16x16x32_bf16 v[124:127], v[148:151], v[190:193], v[124:127]
	v_mfma_f32_16x16x32_bf16 v[120:123], v[156:159], v[190:193], v[120:123]
	v_mfma_f32_16x16x32_bf16 v[116:119], v[148:151], v[212:215], v[116:119]
	v_mfma_f32_16x16x32_bf16 v[112:115], v[156:159], v[212:215], v[112:115]
	v_mfma_f32_16x16x32_bf16 v[108:111], v[148:151], v[220:223], v[108:111]
	v_mfma_f32_16x16x32_bf16 v[104:107], v[156:159], v[220:223], v[104:107]
	v_mfma_f32_16x16x32_bf16 v[100:103], v[148:151], v[228:231], v[100:103]
	v_mfma_f32_16x16x32_bf16 v[96:99], v[156:159], v[228:231], v[96:99]
	v_mfma_f32_16x16x32_bf16 v[124:127], v[152:155], v[208:211], v[124:127]
	v_mfma_f32_16x16x32_bf16 v[120:123], v[160:163], v[208:211], v[120:123]
	v_mfma_f32_16x16x32_bf16 v[116:119], v[152:155], v[216:219], v[116:119]
	v_mfma_f32_16x16x32_bf16 v[112:115], v[160:163], v[216:219], v[112:115]
	v_mfma_f32_16x16x32_bf16 v[108:111], v[152:155], v[224:227], v[108:111]
	v_mfma_f32_16x16x32_bf16 v[104:107], v[160:163], v[224:227], v[104:107]
	v_mfma_f32_16x16x32_bf16 v[100:103], v[152:155], v[232:235], v[100:103]
	v_mfma_f32_16x16x32_bf16 v[96:99], v[160:163], v[232:235], v[96:99]
	s_setprio 0
	s_setprio 1
	v_mfma_f32_16x16x32_bf16 v[92:95], v[174:177], v[190:193], v[92:95]
	v_mfma_f32_16x16x32_bf16 v[88:91], v[182:185], v[190:193], v[88:91]
	v_mfma_f32_16x16x32_bf16 v[84:87], v[174:177], v[212:215], v[84:87]
	v_mfma_f32_16x16x32_bf16 v[80:83], v[182:185], v[212:215], v[80:83]
	v_mfma_f32_16x16x32_bf16 v[76:79], v[174:177], v[220:223], v[76:79]
	v_mfma_f32_16x16x32_bf16 v[72:75], v[182:185], v[220:223], v[72:75]
	v_mfma_f32_16x16x32_bf16 v[68:71], v[174:177], v[228:231], v[68:71]
	v_mfma_f32_16x16x32_bf16 v[64:67], v[182:185], v[228:231], v[64:67]
	v_mfma_f32_16x16x32_bf16 v[92:95], v[178:181], v[208:211], v[92:95]
	v_mfma_f32_16x16x32_bf16 v[88:91], v[186:189], v[208:211], v[88:91]
	v_mfma_f32_16x16x32_bf16 v[84:87], v[178:181], v[216:219], v[84:87]
	v_mfma_f32_16x16x32_bf16 v[80:83], v[186:189], v[216:219], v[80:83]
	v_mfma_f32_16x16x32_bf16 v[76:79], v[178:181], v[224:227], v[76:79]
	v_mfma_f32_16x16x32_bf16 v[72:75], v[186:189], v[224:227], v[72:75]
	v_mfma_f32_16x16x32_bf16 v[68:71], v[178:181], v[232:235], v[68:71]
	v_mfma_f32_16x16x32_bf16 v[64:67], v[186:189], v[232:235], v[64:67]
	s_setprio 0
	s_barrier
	v_lshl_add_u64 v[240:241], v[128:129], 0, s[62:63]
	s_mov_b32 m0, s2
	v_lshl_add_u64 v[242:243], v[240:241], 0, s[46:47]
	ds_read_b128 v[190:193], v195 offset:16384
	ds_read_b128 v[208:211], v195 offset:17408
	ds_read_b128 v[212:215], v195 offset:18432
	ds_read_b128 v[216:219], v195 offset:19456
	ds_read_b128 v[220:223], v195 offset:20480
	ds_read_b128 v[224:227], v195 offset:21504
	ds_read_b128 v[228:231], v195 offset:22528
	ds_read_b128 v[232:235], v195 offset:23552
	global_load_lds_dwordx4 v[242:243], off
	v_lshl_add_u64 v[242:243], v[130:131], 0, s[62:63]
	v_lshl_add_u64 v[244:245], v[242:243], 0, s[46:47]
	s_mov_b32 m0, s16
	s_nop 0
	global_load_lds_dwordx4 v[244:245], off
	v_lshl_add_u64 v[244:245], v[138:139], 0, s[62:63]
	v_lshl_add_u64 v[246:247], v[244:245], 0, s[46:47]
	s_mov_b32 m0, s17
	s_nop 0
	global_load_lds_dwordx4 v[246:247], off
	v_lshl_add_u64 v[246:247], v[136:137], 0, s[62:63]
	v_lshl_add_u64 v[248:249], v[246:247], 0, s[46:47]
	s_mov_b32 m0, s14
	s_nop 0
	global_load_lds_dwordx4 v[248:249], off
	v_lshl_add_u64 v[248:249], v[132:133], 0, s[62:63]
	v_lshl_add_u64 v[250:251], v[248:249], 0, s[46:47]
	s_mov_b32 m0, s89
	s_nop 0
	global_load_lds_dwordx4 v[250:251], off
	v_lshl_add_u64 v[250:251], v[134:135], 0, s[62:63]
	v_lshl_add_u64 v[166:167], v[250:251], 0, s[46:47]
	s_mov_b32 m0, s90
	s_nop 0
	global_load_lds_dwordx4 v[166:167], off
	s_waitcnt vmcnt(8)
	s_waitcnt lgkmcnt(0)
	s_barrier
	s_setprio 1
	s_waitcnt lgkmcnt(0)
	v_mfma_f32_16x16x32_bf16 v[60:63], v[148:151], v[190:193], v[60:63]
	v_mfma_f32_16x16x32_bf16 v[56:59], v[156:159], v[190:193], v[56:59]
	v_mfma_f32_16x16x32_bf16 v[52:55], v[148:151], v[212:215], v[52:55]
	v_mfma_f32_16x16x32_bf16 v[48:51], v[156:159], v[212:215], v[48:51]
	v_mfma_f32_16x16x32_bf16 v[44:47], v[148:151], v[220:223], v[44:47]
	v_mfma_f32_16x16x32_bf16 v[40:43], v[156:159], v[220:223], v[40:43]
	v_mfma_f32_16x16x32_bf16 v[36:39], v[148:151], v[228:231], v[36:39]
	v_mfma_f32_16x16x32_bf16 v[32:35], v[156:159], v[228:231], v[32:35]
	v_mfma_f32_16x16x32_bf16 v[60:63], v[152:155], v[208:211], v[60:63]
	v_mfma_f32_16x16x32_bf16 v[56:59], v[160:163], v[208:211], v[56:59]
	v_mfma_f32_16x16x32_bf16 v[52:55], v[152:155], v[216:219], v[52:55]
	v_mfma_f32_16x16x32_bf16 v[48:51], v[160:163], v[216:219], v[48:51]
	v_mfma_f32_16x16x32_bf16 v[44:47], v[152:155], v[224:227], v[44:47]
	v_mfma_f32_16x16x32_bf16 v[40:43], v[160:163], v[224:227], v[40:43]
	v_mfma_f32_16x16x32_bf16 v[36:39], v[152:155], v[232:235], v[36:39]
	v_mfma_f32_16x16x32_bf16 v[32:35], v[160:163], v[232:235], v[32:35]
	s_setprio 0
	s_setprio 1
	v_mfma_f32_16x16x32_bf16 v[28:31], v[174:177], v[190:193], v[28:31]
	v_mfma_f32_16x16x32_bf16 v[24:27], v[182:185], v[190:193], v[24:27]
	v_mfma_f32_16x16x32_bf16 v[20:23], v[174:177], v[212:215], v[20:23]
	v_mfma_f32_16x16x32_bf16 v[16:19], v[182:185], v[212:215], v[16:19]
	v_mfma_f32_16x16x32_bf16 v[12:15], v[174:177], v[220:223], v[12:15]
	v_mfma_f32_16x16x32_bf16 v[8:11], v[182:185], v[220:223], v[8:11]
	v_mfma_f32_16x16x32_bf16 v[4:7], v[174:177], v[228:231], v[4:7]
	v_mfma_f32_16x16x32_bf16 v[0:3], v[182:185], v[228:231], v[0:3]
	v_mfma_f32_16x16x32_bf16 v[28:31], v[178:181], v[208:211], v[28:31]
	v_mfma_f32_16x16x32_bf16 v[24:27], v[186:189], v[208:211], v[24:27]
	v_mfma_f32_16x16x32_bf16 v[20:23], v[178:181], v[216:219], v[20:23]
	v_mfma_f32_16x16x32_bf16 v[16:19], v[186:189], v[216:219], v[16:19]
	v_mfma_f32_16x16x32_bf16 v[12:15], v[178:181], v[224:227], v[12:15]
	v_mfma_f32_16x16x32_bf16 v[8:11], v[186:189], v[224:227], v[8:11]
	v_mfma_f32_16x16x32_bf16 v[4:7], v[178:181], v[232:235], v[4:7]
	v_mfma_f32_16x16x32_bf16 v[0:3], v[186:189], v[232:235], v[0:3]
	s_setprio 0
	s_barrier
	ds_read_b128 v[148:151], v146
	ds_read_b128 v[152:155], v146 offset:1024
	ds_read_b128 v[156:159], v146 offset:2048
	ds_read_b128 v[160:163], v146 offset:3072
	ds_read_b128 v[174:177], v147
	ds_read_b128 v[178:181], v147 offset:1024
	ds_read_b128 v[182:185], v147 offset:2048
	ds_read_b128 v[186:189], v147 offset:3072
	s_mov_b32 m0, s91
	v_lshl_add_u64 v[166:167], v[236:237], 0, s[46:47]
	ds_read_b128 v[190:193], v195 offset:32768
	ds_read_b128 v[208:211], v195 offset:33792
	ds_read_b128 v[212:215], v195 offset:34816
	ds_read_b128 v[216:219], v195 offset:35840
	ds_read_b128 v[220:223], v195 offset:36864
	ds_read_b128 v[224:227], v195 offset:37888
	ds_read_b128 v[228:231], v195 offset:38912
	ds_read_b128 v[232:235], v195 offset:39936
	global_load_lds_dwordx4 v[166:167], off
	v_lshl_add_u64 v[166:167], v[238:239], 0, s[46:47]
	s_mov_b32 m0, s92
	s_nop 0
	global_load_lds_dwordx4 v[166:167], off
	s_waitcnt vmcnt(8)
	s_waitcnt lgkmcnt(0)
	s_barrier
	s_setprio 1
	s_waitcnt lgkmcnt(0)
	v_mfma_f32_16x16x32_bf16 v[124:127], v[148:151], v[190:193], v[124:127]
	v_mfma_f32_16x16x32_bf16 v[120:123], v[156:159], v[190:193], v[120:123]
	v_mfma_f32_16x16x32_bf16 v[116:119], v[148:151], v[212:215], v[116:119]
	v_mfma_f32_16x16x32_bf16 v[112:115], v[156:159], v[212:215], v[112:115]
	v_mfma_f32_16x16x32_bf16 v[108:111], v[148:151], v[220:223], v[108:111]
	v_mfma_f32_16x16x32_bf16 v[104:107], v[156:159], v[220:223], v[104:107]
	v_mfma_f32_16x16x32_bf16 v[100:103], v[148:151], v[228:231], v[100:103]
	v_mfma_f32_16x16x32_bf16 v[96:99], v[156:159], v[228:231], v[96:99]
	v_mfma_f32_16x16x32_bf16 v[124:127], v[152:155], v[208:211], v[124:127]
	v_mfma_f32_16x16x32_bf16 v[120:123], v[160:163], v[208:211], v[120:123]
	v_mfma_f32_16x16x32_bf16 v[116:119], v[152:155], v[216:219], v[116:119]
	v_mfma_f32_16x16x32_bf16 v[112:115], v[160:163], v[216:219], v[112:115]
	v_mfma_f32_16x16x32_bf16 v[108:111], v[152:155], v[224:227], v[108:111]
	v_mfma_f32_16x16x32_bf16 v[104:107], v[160:163], v[224:227], v[104:107]
	v_mfma_f32_16x16x32_bf16 v[100:103], v[152:155], v[232:235], v[100:103]
	v_mfma_f32_16x16x32_bf16 v[96:99], v[160:163], v[232:235], v[96:99]
	s_setprio 0
	s_setprio 1
	v_mfma_f32_16x16x32_bf16 v[92:95], v[174:177], v[190:193], v[92:95]
	v_mfma_f32_16x16x32_bf16 v[88:91], v[182:185], v[190:193], v[88:91]
	v_mfma_f32_16x16x32_bf16 v[84:87], v[174:177], v[212:215], v[84:87]
	v_mfma_f32_16x16x32_bf16 v[80:83], v[182:185], v[212:215], v[80:83]
	v_mfma_f32_16x16x32_bf16 v[76:79], v[174:177], v[220:223], v[76:79]
	v_mfma_f32_16x16x32_bf16 v[72:75], v[182:185], v[220:223], v[72:75]
	v_mfma_f32_16x16x32_bf16 v[68:71], v[174:177], v[228:231], v[68:71]
	v_mfma_f32_16x16x32_bf16 v[64:67], v[182:185], v[228:231], v[64:67]
	v_mfma_f32_16x16x32_bf16 v[92:95], v[178:181], v[208:211], v[92:95]
	v_mfma_f32_16x16x32_bf16 v[88:91], v[186:189], v[208:211], v[88:91]
	v_mfma_f32_16x16x32_bf16 v[84:87], v[178:181], v[216:219], v[84:87]
	v_mfma_f32_16x16x32_bf16 v[80:83], v[186:189], v[216:219], v[80:83]
	v_mfma_f32_16x16x32_bf16 v[76:79], v[178:181], v[224:227], v[76:79]
	v_mfma_f32_16x16x32_bf16 v[72:75], v[186:189], v[224:227], v[72:75]
	v_mfma_f32_16x16x32_bf16 v[68:71], v[178:181], v[232:235], v[68:71]
	v_mfma_f32_16x16x32_bf16 v[64:67], v[186:189], v[232:235], v[64:67]
	s_setprio 0
	s_barrier
	s_mov_b32 m0, s15
	v_lshl_add_u64 v[166:167], v[240:241], 0, s[48:49]
	ds_read_b128 v[190:193], v195 offset:49152
	ds_read_b128 v[208:211], v195 offset:50176
	ds_read_b128 v[212:215], v195 offset:51200
	ds_read_b128 v[216:219], v195 offset:52224
	ds_read_b128 v[220:223], v195 offset:53248
	ds_read_b128 v[224:227], v195 offset:54272
	ds_read_b128 v[228:231], v195 offset:55296
	ds_read_b128 v[232:235], v195 offset:56320
	global_load_lds_dwordx4 v[166:167], off
	v_lshl_add_u64 v[166:167], v[242:243], 0, s[48:49]
	s_mov_b32 m0, s33
	s_nop 0
	global_load_lds_dwordx4 v[166:167], off
	v_lshl_add_u64 v[166:167], v[244:245], 0, s[48:49]
	s_mov_b32 m0, s3
	s_nop 0
	global_load_lds_dwordx4 v[166:167], off
	v_lshl_add_u64 v[166:167], v[246:247], 0, s[48:49]
	s_mov_b32 m0, s20
	s_nop 0
	global_load_lds_dwordx4 v[166:167], off
	v_lshl_add_u64 v[166:167], v[248:249], 0, s[48:49]
	s_mov_b32 m0, s93
	s_nop 0
	global_load_lds_dwordx4 v[166:167], off
	v_lshl_add_u64 v[166:167], v[250:251], 0, s[48:49]
	s_mov_b32 m0, s94
	s_nop 0
	global_load_lds_dwordx4 v[166:167], off
	s_waitcnt vmcnt(8)
	s_waitcnt lgkmcnt(0)
	s_barrier
	s_setprio 1
	s_waitcnt lgkmcnt(0)
	v_mfma_f32_16x16x32_bf16 v[60:63], v[148:151], v[190:193], v[60:63]
	v_mfma_f32_16x16x32_bf16 v[56:59], v[156:159], v[190:193], v[56:59]
	v_mfma_f32_16x16x32_bf16 v[52:55], v[148:151], v[212:215], v[52:55]
	v_mfma_f32_16x16x32_bf16 v[48:51], v[156:159], v[212:215], v[48:51]
	v_mfma_f32_16x16x32_bf16 v[44:47], v[148:151], v[220:223], v[44:47]
	v_mfma_f32_16x16x32_bf16 v[40:43], v[156:159], v[220:223], v[40:43]
	v_mfma_f32_16x16x32_bf16 v[36:39], v[148:151], v[228:231], v[36:39]
	v_mfma_f32_16x16x32_bf16 v[32:35], v[156:159], v[228:231], v[32:35]
	v_mfma_f32_16x16x32_bf16 v[60:63], v[152:155], v[208:211], v[60:63]
	v_mfma_f32_16x16x32_bf16 v[56:59], v[160:163], v[208:211], v[56:59]
	v_mfma_f32_16x16x32_bf16 v[52:55], v[152:155], v[216:219], v[52:55]
	v_mfma_f32_16x16x32_bf16 v[48:51], v[160:163], v[216:219], v[48:51]
	v_mfma_f32_16x16x32_bf16 v[44:47], v[152:155], v[224:227], v[44:47]
	v_mfma_f32_16x16x32_bf16 v[40:43], v[160:163], v[224:227], v[40:43]
	v_mfma_f32_16x16x32_bf16 v[36:39], v[152:155], v[232:235], v[36:39]
	v_mfma_f32_16x16x32_bf16 v[32:35], v[160:163], v[232:235], v[32:35]
	s_setprio 0
	s_setprio 1
	v_mfma_f32_16x16x32_bf16 v[28:31], v[174:177], v[190:193], v[28:31]
	v_mfma_f32_16x16x32_bf16 v[24:27], v[182:185], v[190:193], v[24:27]
	v_mfma_f32_16x16x32_bf16 v[20:23], v[174:177], v[212:215], v[20:23]
	s_add_u32 s62, s62, 0x100
	v_mfma_f32_16x16x32_bf16 v[16:19], v[182:185], v[212:215], v[16:19]
	s_addc_u32 s63, s63, 0
	v_mfma_f32_16x16x32_bf16 v[12:15], v[174:177], v[220:223], v[12:15]
	s_add_i32 s32, s22, 2
	v_mfma_f32_16x16x32_bf16 v[8:11], v[182:185], v[220:223], v[8:11]
	s_add_i32 s99, s22, -4
	v_mfma_f32_16x16x32_bf16 v[4:7], v[174:177], v[228:231], v[4:7]
	s_cmp_ge_i32 s99, s29
	v_mfma_f32_16x16x32_bf16 v[0:3], v[182:185], v[228:231], v[0:3]
	s_cselect_b32 s98, 0, 1
	v_mfma_f32_16x16x32_bf16 v[28:31], v[178:181], v[208:211], v[28:31]
	s_cmp_eq_u32 s34, s32
	v_mfma_f32_16x16x32_bf16 v[24:27], v[186:189], v[208:211], v[24:27]
	s_cselect_b64 vcc, -1, 0
	v_mfma_f32_16x16x32_bf16 v[20:23], v[178:181], v[216:219], v[20:23]
	s_and_b64 vcc, s[66:67], vcc
	v_mfma_f32_16x16x32_bf16 v[16:19], v[186:189], v[216:219], v[16:19]
	s_cselect_b32 s98, 0, s98
	v_mfma_f32_16x16x32_bf16 v[12:15], v[178:181], v[224:227], v[12:15]
	s_and_b64 vcc, exec, s[8:9]
	v_mfma_f32_16x16x32_bf16 v[8:11], v[186:189], v[224:227], v[8:11]
	s_cselect_b32 s98, s98, 0
	v_mfma_f32_16x16x32_bf16 v[4:7], v[178:181], v[232:235], v[4:7]
	s_cmp_lg_u32 s98, 0
	v_mfma_f32_16x16x32_bf16 v[0:3], v[186:189], v[232:235], v[0:3]
	s_setprio 0
	s_barrier
	s_cbranch_scc1 .Lk_fastb
	s_and_b64 vcc, exec, s[8:9]
	s_cbranch_vccnz .LBB0_394
	s_waitcnt vmcnt(16)
	v_mov_b32_e32 v148, s82
	v_mov_b32_e32 v149, s21
	ds_read_b32 v148, v148
	ds_read_b32 v149, v149 offset:60
	s_mov_b64 s[64:65], 0
	s_waitcnt lgkmcnt(0)
	v_readfirstlane_b32 s8, v148
	v_readfirstlane_b32 s9, v149
	s_mul_i32 s9, s9, s28
	s_cmp_lt_u32 s8, s9
	s_cbranch_scc1 .LBB0_394
	buffer_inv sc1
	s_mov_b64 s[64:65], -1
.LBB0_394:
	s_add_i32 s8, s22, 2
	s_add_i32 s9, s22, -4
	s_cmp_ge_i32 s9, s29
	s_cbranch_scc1 .LBB0_396
	s_mov_b32 s22, s8
	s_branch .LBB0_387

.LBB0_2161:
	v_cndmask_b32_e64 v150, 0, 1, s[58:59]
	v_cmp_ne_u32_e64 s[10:11], 1, v150
	s_andn2_b64 vcc, exec, s[58:59]
	s_cbranch_vccnz .LBB0_2163
	s_mov_b32 m0, s50
	s_nop 0
	global_load_lds_dword v1, s[30:31] sc1
	s_branch .LBB0_2163
.Lk_fasta:
	s_mov_b32 s62, s32
.LBB0_2163:
	ds_read_b128 v[150:153], v146
	ds_read_b128 v[154:157], v146 offset:1024
	ds_read_b128 v[158:161], v146 offset:2048
	ds_read_b128 v[162:165], v146 offset:3072
	ds_read_b128 v[166:169], v147
	ds_read_b128 v[180:183], v147 offset:1024
	ds_read_b128 v[184:187], v147 offset:2048
	ds_read_b128 v[188:191], v147 offset:3072
	v_lshl_add_u64 v[242:243], v[144:145], 0, s[38:39]
	s_mov_b32 m0, s95
	v_lshl_add_u64 v[244:245], v[242:243], 0, s[78:79]
	ds_read_b128 v[192:195], v200
	ds_read_b128 v[196:199], v200 offset:1024
	ds_read_b128 v[218:221], v200 offset:2048
	ds_read_b128 v[222:225], v200 offset:3072
	ds_read_b128 v[226:229], v200 offset:4096
	ds_read_b128 v[230:233], v200 offset:5120
	ds_read_b128 v[234:237], v200 offset:6144
	ds_read_b128 v[238:241], v200 offset:7168
	global_load_lds_dwordx4 v[244:245], off
	v_lshl_add_u64 v[244:245], v[142:143], 0, s[38:39]
	v_lshl_add_u64 v[246:247], v[244:245], 0, s[78:79]
	s_mov_b32 m0, s96
	s_nop 0
	global_load_lds_dwordx4 v[246:247], off
	s_waitcnt vmcnt(8)
	s_waitcnt lgkmcnt(0)
	s_barrier
	s_setprio 1
	s_waitcnt lgkmcnt(0)
	v_mfma_f32_16x16x32_bf16 v[126:129], v[150:153], v[192:195], v[126:129]
	v_mfma_f32_16x16x32_bf16 v[122:125], v[158:161], v[192:195], v[122:125]
	v_mfma_f32_16x16x32_bf16 v[118:121], v[150:153], v[218:221], v[118:121]
	v_mfma_f32_16x16x32_bf16 v[114:117], v[158:161], v[218:221], v[114:117]
	v_mfma_f32_16x16x32_bf16 v[110:113], v[150:153], v[226:229], v[110:113]
	v_mfma_f32_16x16x32_bf16 v[106:109], v[158:161], v[226:229], v[106:109]
	v_mfma_f32_16x16x32_bf16 v[102:105], v[150:153], v[234:237], v[102:105]
	v_mfma_f32_16x16x32_bf16 v[98:101], v[158:161], v[234:237], v[98:101]
	v_mfma_f32_16x16x32_bf16 v[126:129], v[154:157], v[196:199], v[126:129]
	v_mfma_f32_16x16x32_bf16 v[122:125], v[162:165], v[196:199], v[122:125]
	v_mfma_f32_16x16x32_bf16 v[118:121], v[154:157], v[222:225], v[118:121]
	v_mfma_f32_16x16x32_bf16 v[114:117], v[162:165], v[222:225], v[114:117]
	v_mfma_f32_16x16x32_bf16 v[110:113], v[154:157], v[230:233], v[110:113]
	v_mfma_f32_16x16x32_bf16 v[106:109], v[162:165], v[230:233], v[106:109]
	v_mfma_f32_16x16x32_bf16 v[102:105], v[154:157], v[238:241], v[102:105]
	v_mfma_f32_16x16x32_bf16 v[98:101], v[162:165], v[238:241], v[98:101]
	s_setprio 0
	s_setprio 1
	v_mfma_f32_16x16x32_bf16 v[94:97], v[166:169], v[192:195], v[94:97]
	v_mfma_f32_16x16x32_bf16 v[90:93], v[184:187], v[192:195], v[90:93]
	v_mfma_f32_16x16x32_bf16 v[86:89], v[166:169], v[218:221], v[86:89]
	v_mfma_f32_16x16x32_bf16 v[82:85], v[184:187], v[218:221], v[82:85]
	v_mfma_f32_16x16x32_bf16 v[78:81], v[166:169], v[226:229], v[78:81]
	v_mfma_f32_16x16x32_bf16 v[74:77], v[184:187], v[226:229], v[74:77]
	v_mfma_f32_16x16x32_bf16 v[70:73], v[166:169], v[234:237], v[70:73]
	v_mfma_f32_16x16x32_bf16 v[66:69], v[184:187], v[234:237], v[66:69]
	v_mfma_f32_16x16x32_bf16 v[94:97], v[180:183], v[196:199], v[94:97]
	v_mfma_f32_16x16x32_bf16 v[90:93], v[188:191], v[196:199], v[90:93]
	v_mfma_f32_16x16x32_bf16 v[86:89], v[180:183], v[222:225], v[86:89]
	v_mfma_f32_16x16x32_bf16 v[82:85], v[188:191], v[222:225], v[82:85]
	v_mfma_f32_16x16x32_bf16 v[78:81], v[180:183], v[230:233], v[78:81]
	v_mfma_f32_16x16x32_bf16 v[74:77], v[188:191], v[230:233], v[74:77]
	v_mfma_f32_16x16x32_bf16 v[70:73], v[180:183], v[238:241], v[70:73]
	v_mfma_f32_16x16x32_bf16 v[66:69], v[188:191], v[238:241], v[66:69]
	s_setprio 0
	s_barrier
	v_lshl_add_u64 v[246:247], v[130:131], 0, s[38:39]
	s_mov_b32 m0, s2
	v_lshl_add_u64 v[248:249], v[246:247], 0, s[76:77]
	ds_read_b128 v[192:195], v200 offset:16384
	ds_read_b128 v[196:199], v200 offset:17408
	ds_read_b128 v[218:221], v200 offset:18432
	ds_read_b128 v[222:225], v200 offset:19456
	ds_read_b128 v[226:229], v200 offset:20480
	ds_read_b128 v[230:233], v200 offset:21504
	ds_read_b128 v[234:237], v200 offset:22528
	ds_read_b128 v[238:241], v200 offset:23552
	global_load_lds_dwordx4 v[248:249], off
	v_lshl_add_u64 v[248:249], v[132:133], 0, s[38:39]
	v_lshl_add_u64 v[250:251], v[248:249], 0, s[76:77]
	s_mov_b32 m0, s56
	s_nop 0
	global_load_lds_dwordx4 v[250:251], off
	v_lshl_add_u64 v[250:251], v[140:141], 0, s[38:39]
	v_lshl_add_u64 v[206:207], v[250:251], 0, s[76:77]
	s_mov_b32 m0, s19
	s_nop 0
	global_load_lds_dwordx4 v[206:207], off
	v_lshl_add_u64 v[206:207], v[138:139], 0, s[38:39]
	v_lshl_add_u64 v[204:205], v[206:207], 0, s[76:77]
	s_mov_b32 m0, s63
	s_nop 0
	global_load_lds_dwordx4 v[204:205], off
	v_lshl_add_u64 v[204:205], v[134:135], 0, s[38:39]
	v_lshl_add_u64 v[170:171], v[204:205], 0, s[76:77]
	s_mov_b32 m0, s53
	s_nop 0
	global_load_lds_dwordx4 v[170:171], off
	v_lshl_add_u64 v[170:171], v[136:137], 0, s[38:39]
	v_lshl_add_u64 v[208:209], v[170:171], 0, s[76:77]
	s_mov_b32 m0, s92
	s_nop 0
	global_load_lds_dwordx4 v[208:209], off
	s_waitcnt vmcnt(8)
	s_waitcnt lgkmcnt(0)
	s_barrier
	s_setprio 1
	s_waitcnt lgkmcnt(0)
	v_mfma_f32_16x16x32_bf16 v[62:65], v[150:153], v[192:195], v[62:65]
	v_mfma_f32_16x16x32_bf16 v[58:61], v[158:161], v[192:195], v[58:61]
	v_mfma_f32_16x16x32_bf16 v[54:57], v[150:153], v[218:221], v[54:57]
	v_mfma_f32_16x16x32_bf16 v[50:53], v[158:161], v[218:221], v[50:53]
	v_mfma_f32_16x16x32_bf16 v[46:49], v[150:153], v[226:229], v[46:49]
	v_mfma_f32_16x16x32_bf16 v[42:45], v[158:161], v[226:229], v[42:45]
	v_mfma_f32_16x16x32_bf16 v[38:41], v[150:153], v[234:237], v[38:41]
	v_mfma_f32_16x16x32_bf16 v[34:37], v[158:161], v[234:237], v[34:37]
	v_mfma_f32_16x16x32_bf16 v[62:65], v[154:157], v[196:199], v[62:65]
	v_mfma_f32_16x16x32_bf16 v[58:61], v[162:165], v[196:199], v[58:61]
	v_mfma_f32_16x16x32_bf16 v[54:57], v[154:157], v[222:225], v[54:57]
	v_mfma_f32_16x16x32_bf16 v[50:53], v[162:165], v[222:225], v[50:53]
	v_mfma_f32_16x16x32_bf16 v[46:49], v[154:157], v[230:233], v[46:49]
	v_mfma_f32_16x16x32_bf16 v[42:45], v[162:165], v[230:233], v[42:45]
	v_mfma_f32_16x16x32_bf16 v[38:41], v[154:157], v[238:241], v[38:41]
	v_mfma_f32_16x16x32_bf16 v[34:37], v[162:165], v[238:241], v[34:37]
	s_setprio 0
	s_setprio 1
	v_mfma_f32_16x16x32_bf16 v[30:33], v[166:169], v[192:195], v[30:33]
	v_mfma_f32_16x16x32_bf16 v[26:29], v[184:187], v[192:195], v[26:29]
	v_mfma_f32_16x16x32_bf16 v[22:25], v[166:169], v[218:221], v[22:25]
	v_mfma_f32_16x16x32_bf16 v[18:21], v[184:187], v[218:221], v[18:21]
	v_mfma_f32_16x16x32_bf16 v[14:17], v[166:169], v[226:229], v[14:17]
	v_mfma_f32_16x16x32_bf16 v[10:13], v[184:187], v[226:229], v[10:13]
	v_mfma_f32_16x16x32_bf16 v[6:9], v[166:169], v[234:237], v[6:9]
	v_mfma_f32_16x16x32_bf16 v[2:5], v[184:187], v[234:237], v[2:5]
	v_mfma_f32_16x16x32_bf16 v[30:33], v[180:183], v[196:199], v[30:33]
	v_mfma_f32_16x16x32_bf16 v[26:29], v[188:191], v[196:199], v[26:29]
	v_mfma_f32_16x16x32_bf16 v[22:25], v[180:183], v[222:225], v[22:25]
	v_mfma_f32_16x16x32_bf16 v[18:21], v[188:191], v[222:225], v[18:21]
	v_mfma_f32_16x16x32_bf16 v[14:17], v[180:183], v[230:233], v[14:17]
	v_mfma_f32_16x16x32_bf16 v[10:13], v[188:191], v[230:233], v[10:13]
	v_mfma_f32_16x16x32_bf16 v[6:9], v[180:183], v[238:241], v[6:9]
	v_mfma_f32_16x16x32_bf16 v[2:5], v[188:191], v[238:241], v[2:5]
	s_setprio 0
	s_barrier
	ds_read_b128 v[150:153], v148
	ds_read_b128 v[154:157], v148 offset:1024
	ds_read_b128 v[158:161], v148 offset:2048
	ds_read_b128 v[162:165], v148 offset:3072
	ds_read_b128 v[166:169], v149
	ds_read_b128 v[180:183], v149 offset:1024
	ds_read_b128 v[184:187], v149 offset:2048
	ds_read_b128 v[188:191], v149 offset:3072
	s_mov_b32 m0, s93
	v_lshl_add_u64 v[208:209], v[242:243], 0, s[76:77]
	ds_read_b128 v[192:195], v200 offset:32768
	ds_read_b128 v[196:199], v200 offset:33792
	ds_read_b128 v[218:221], v200 offset:34816
	ds_read_b128 v[222:225], v200 offset:35840
	ds_read_b128 v[226:229], v200 offset:36864
	ds_read_b128 v[230:233], v200 offset:37888
	ds_read_b128 v[234:237], v200 offset:38912
	ds_read_b128 v[238:241], v200 offset:39936
	global_load_lds_dwordx4 v[208:209], off
	v_lshl_add_u64 v[208:209], v[244:245], 0, s[76:77]
	s_mov_b32 m0, s54
	s_nop 0
	global_load_lds_dwordx4 v[208:209], off
	s_waitcnt vmcnt(8)
	s_waitcnt lgkmcnt(0)
	s_barrier
	s_setprio 1
	s_waitcnt lgkmcnt(0)
	v_mfma_f32_16x16x32_bf16 v[126:129], v[150:153], v[192:195], v[126:129]
	v_mfma_f32_16x16x32_bf16 v[122:125], v[158:161], v[192:195], v[122:125]
	v_mfma_f32_16x16x32_bf16 v[118:121], v[150:153], v[218:221], v[118:121]
	v_mfma_f32_16x16x32_bf16 v[114:117], v[158:161], v[218:221], v[114:117]
	v_mfma_f32_16x16x32_bf16 v[110:113], v[150:153], v[226:229], v[110:113]
	v_mfma_f32_16x16x32_bf16 v[106:109], v[158:161], v[226:229], v[106:109]
	v_mfma_f32_16x16x32_bf16 v[102:105], v[150:153], v[234:237], v[102:105]
	v_mfma_f32_16x16x32_bf16 v[98:101], v[158:161], v[234:237], v[98:101]
	v_mfma_f32_16x16x32_bf16 v[126:129], v[154:157], v[196:199], v[126:129]
	v_mfma_f32_16x16x32_bf16 v[122:125], v[162:165], v[196:199], v[122:125]
	v_mfma_f32_16x16x32_bf16 v[118:121], v[154:157], v[222:225], v[118:121]
	v_mfma_f32_16x16x32_bf16 v[114:117], v[162:165], v[222:225], v[114:117]
	v_mfma_f32_16x16x32_bf16 v[110:113], v[154:157], v[230:233], v[110:113]
	v_mfma_f32_16x16x32_bf16 v[106:109], v[162:165], v[230:233], v[106:109]
	v_mfma_f32_16x16x32_bf16 v[102:105], v[154:157], v[238:241], v[102:105]
	v_mfma_f32_16x16x32_bf16 v[98:101], v[162:165], v[238:241], v[98:101]
	s_setprio 0
	s_setprio 1
	v_mfma_f32_16x16x32_bf16 v[94:97], v[166:169], v[192:195], v[94:97]
	v_mfma_f32_16x16x32_bf16 v[90:93], v[184:187], v[192:195], v[90:93]
	v_mfma_f32_16x16x32_bf16 v[86:89], v[166:169], v[218:221], v[86:89]
	v_mfma_f32_16x16x32_bf16 v[82:85], v[184:187], v[218:221], v[82:85]
	v_mfma_f32_16x16x32_bf16 v[78:81], v[166:169], v[226:229], v[78:81]
	v_mfma_f32_16x16x32_bf16 v[74:77], v[184:187], v[226:229], v[74:77]
	v_mfma_f32_16x16x32_bf16 v[70:73], v[166:169], v[234:237], v[70:73]
	v_mfma_f32_16x16x32_bf16 v[66:69], v[184:187], v[234:237], v[66:69]
	v_mfma_f32_16x16x32_bf16 v[94:97], v[180:183], v[196:199], v[94:97]
	v_mfma_f32_16x16x32_bf16 v[90:93], v[188:191], v[196:199], v[90:93]
	v_mfma_f32_16x16x32_bf16 v[86:89], v[180:183], v[222:225], v[86:89]
	v_mfma_f32_16x16x32_bf16 v[82:85], v[188:191], v[222:225], v[82:85]
	v_mfma_f32_16x16x32_bf16 v[78:81], v[180:183], v[230:233], v[78:81]
	v_mfma_f32_16x16x32_bf16 v[74:77], v[188:191], v[230:233], v[74:77]
	v_mfma_f32_16x16x32_bf16 v[70:73], v[180:183], v[238:241], v[70:73]
	v_mfma_f32_16x16x32_bf16 v[66:69], v[188:191], v[238:241], v[66:69]
	s_setprio 0
	s_barrier
	s_mov_b32 m0, s33
	v_lshl_add_u64 v[208:209], v[246:247], 0, s[80:81]
	ds_read_b128 v[192:195], v200 offset:49152
	ds_read_b128 v[196:199], v200 offset:50176
	ds_read_b128 v[218:221], v200 offset:51200
	ds_read_b128 v[222:225], v200 offset:52224
	ds_read_b128 v[226:229], v200 offset:53248
	ds_read_b128 v[230:233], v200 offset:54272
	ds_read_b128 v[234:237], v200 offset:55296
	ds_read_b128 v[238:241], v200 offset:56320
	global_load_lds_dwordx4 v[208:209], off
	v_lshl_add_u64 v[208:209], v[248:249], 0, s[80:81]
	s_mov_b32 m0, s3
	v_lshl_add_u64 v[206:207], v[206:207], 0, s[80:81]
	global_load_lds_dwordx4 v[208:209], off
	v_lshl_add_u64 v[208:209], v[250:251], 0, s[80:81]
	s_mov_b32 m0, s47
	v_lshl_add_u64 v[204:205], v[204:205], 0, s[80:81]
	global_load_lds_dwordx4 v[208:209], off
	s_mov_b32 m0, s4
	v_lshl_add_u64 v[170:171], v[170:171], 0, s[80:81]
	global_load_lds_dwordx4 v[206:207], off
	s_mov_b32 m0, s55
	s_nop 0
	global_load_lds_dwordx4 v[204:205], off
	s_mov_b32 m0, s64
	s_nop 0
	global_load_lds_dwordx4 v[170:171], off
	s_waitcnt vmcnt(8)
	s_waitcnt lgkmcnt(0)
	s_barrier
	s_setprio 1
	s_waitcnt lgkmcnt(0)
	v_mfma_f32_16x16x32_bf16 v[62:65], v[150:153], v[192:195], v[62:65]
	v_mfma_f32_16x16x32_bf16 v[58:61], v[158:161], v[192:195], v[58:61]
	v_mfma_f32_16x16x32_bf16 v[54:57], v[150:153], v[218:221], v[54:57]
	v_mfma_f32_16x16x32_bf16 v[50:53], v[158:161], v[218:221], v[50:53]
	v_mfma_f32_16x16x32_bf16 v[46:49], v[150:153], v[226:229], v[46:49]
	v_mfma_f32_16x16x32_bf16 v[42:45], v[158:161], v[226:229], v[42:45]
	v_mfma_f32_16x16x32_bf16 v[38:41], v[150:153], v[234:237], v[38:41]
	v_mfma_f32_16x16x32_bf16 v[34:37], v[158:161], v[234:237], v[34:37]
	v_mfma_f32_16x16x32_bf16 v[62:65], v[154:157], v[196:199], v[62:65]
	v_mfma_f32_16x16x32_bf16 v[58:61], v[162:165], v[196:199], v[58:61]
	v_mfma_f32_16x16x32_bf16 v[54:57], v[154:157], v[222:225], v[54:57]
	v_mfma_f32_16x16x32_bf16 v[50:53], v[162:165], v[222:225], v[50:53]
	v_mfma_f32_16x16x32_bf16 v[46:49], v[154:157], v[230:233], v[46:49]
	v_mfma_f32_16x16x32_bf16 v[42:45], v[162:165], v[230:233], v[42:45]
	v_mfma_f32_16x16x32_bf16 v[38:41], v[154:157], v[238:241], v[38:41]
	v_mfma_f32_16x16x32_bf16 v[34:37], v[162:165], v[238:241], v[34:37]
	s_setprio 0
	s_setprio 1
	v_mfma_f32_16x16x32_bf16 v[30:33], v[166:169], v[192:195], v[30:33]
	v_mfma_f32_16x16x32_bf16 v[26:29], v[184:187], v[192:195], v[26:29]
	v_mfma_f32_16x16x32_bf16 v[22:25], v[166:169], v[218:221], v[22:25]
	s_add_u32 s38, s38, 0x100
	v_mfma_f32_16x16x32_bf16 v[18:21], v[184:187], v[218:221], v[18:21]
	s_addc_u32 s39, s39, 0
	v_mfma_f32_16x16x32_bf16 v[14:17], v[166:169], v[226:229], v[14:17]
	s_add_i32 s32, s62, 2
	v_mfma_f32_16x16x32_bf16 v[10:13], v[184:187], v[226:229], v[10:13]
	s_add_i32 s99, s62, -4
	v_mfma_f32_16x16x32_bf16 v[6:9], v[166:169], v[234:237], v[6:9]
	s_cmp_ge_i32 s99, s51
	v_mfma_f32_16x16x32_bf16 v[2:5], v[184:187], v[234:237], v[2:5]
	s_cselect_b32 s98, 0, 1
	v_mfma_f32_16x16x32_bf16 v[30:33], v[180:183], v[196:199], v[30:33]
	s_cmp_eq_u32 s94, s32
	v_mfma_f32_16x16x32_bf16 v[26:29], v[188:191], v[196:199], v[26:29]
	s_cselect_b64 vcc, -1, 0
	v_mfma_f32_16x16x32_bf16 v[22:25], v[180:183], v[222:225], v[22:25]
	s_and_b64 vcc, s[16:17], vcc
	v_mfma_f32_16x16x32_bf16 v[18:21], v[188:191], v[222:225], v[18:21]
	s_cselect_b32 s98, 0, s98
	v_mfma_f32_16x16x32_bf16 v[14:17], v[180:183], v[230:233], v[14:17]
	s_and_b64 vcc, exec, s[10:11]
	v_mfma_f32_16x16x32_bf16 v[10:13], v[188:191], v[230:233], v[10:13]
	s_cselect_b32 s98, s98, 0
	v_mfma_f32_16x16x32_bf16 v[6:9], v[180:183], v[238:241], v[6:9]
	s_cmp_lg_u32 s98, 0
	v_mfma_f32_16x16x32_bf16 v[2:5], v[188:191], v[238:241], v[2:5]
	s_setprio 0
	s_barrier
	s_cbranch_scc1 .Lk_fasta
	s_and_b64 vcc, exec, s[10:11]
	s_cbranch_vccnz .LBB0_2166
	s_waitcnt vmcnt(16)
	v_mov_b32_e32 v150, s50
	v_mov_b32_e32 v151, s5
	ds_read_b32 v150, v150
	ds_read_b32 v151, v151 offset:60
	s_mov_b64 s[40:41], 0
	s_waitcnt lgkmcnt(0)
	v_readfirstlane_b32 s10, v150
	v_readfirstlane_b32 s11, v151
	s_mul_i32 s11, s11, s18
	s_cmp_lt_u32 s10, s11
	s_cbranch_scc1 .LBB0_2166
	buffer_inv sc1
	s_mov_b64 s[40:41], -1
.LBB0_2166:
	s_add_i32 s10, s62, 2
	s_add_i32 s11, s62, -4
	s_cmp_ge_i32 s11, s51
	s_cbranch_scc1 .LBB0_2168
	s_mov_b32 s62, s10
	s_branch .LBB0_2159
